# v7 + inverse wave priority in the MLA loop: s_setprio 0 over the QK and P.V MFMA clusters, 1 over the softmax VALU section
# speedup vs baseline: 1.0064x; 1.0064x over previous
; #define LAS __attribute__((address_space(3)))
; template <int DK16>
; __device__ __forceinline__ f32x16 qk_sub(const LAS unsigned char* Kt, int ks, int sub, const bf16x8 (&qf)[DK16], int r32, int hi) {
;     f32x16 s;
; #pragma unroll
;     for (int v = 0; v < 16; ++v) s[v] = 0.f;
;     const LAS unsigned char* p = Kt + (sub * 32 + r32) * ks + hi * 16;
; #pragma unroll
;     for (int dk = 0; dk < DK16; ++dk) { const bf16x8 kf = *(const LAS bf16x8*)(p + dk * 32); s = __builtin_amdgcn_mfma_f32_32x32x16_bf16(kf, qf[dk], s, 0, 0, 0); }
;     return s;
; }
; template <int D, int DV, int MODE, bool HASBIAS, bool JOINT, bool DEFER, class KA, class VA, class PF, class BF, class VF, class NM, class WS, class CB> ...
;     ...
;         const bool sk0 = wskip(t, 0), sk1 = wskip(t, 1);
;         if (JOINT && MODE != 2 && !sk0 && !sk1) {
;             f32x16 s0 = qk_sub<D / 16>(cur, KS, 0, qf, r32, hi); if (DEFER) __builtin_amdgcn_sched_barrier(0); f32x16 s1 = qk_sub<D / 16>(cur, KS, 1, qf, r32, hi);
.LBB0_1016:
	s_add_i32 s10, s49, 0xffffff81
	s_cmp_le_i32 s10, s39
	s_cselect_b64 s[8:9], -1, 0
	s_add_i32 s11, s49, 0xffffffa1
	s_cmp_le_i32 s11, s39
	s_cselect_b64 s[18:19], -1, 0
	s_max_i32 s10, s10, s11
	s_cmp_gt_i32 s10, s39
	s_cselect_b64 s[10:11], -1, 0
	s_andn2_b64 vcc, exec, s[10:11]
	s_cbranch_vccz .LBB0_1027
	v_add_u32_e32 v1, v173, v2
	ds_read_b128 v[36:39], v1
	ds_read_b128 v[52:55], v1 offset:32
	s_cmp_ge_u32 s53, s38
	s_cbranch_scc1 .Lmla_qkp1
	s_lshl_b32 s74, s52, 6
	s_mov_b64 s[12:13], 0x340fff80
	s_mov_b64 s[100:101], 0x24120000
	s_add_i32 s10, s49, 0xffffffa0
	s_sub_i32 s11, s49, 64
	s_max_i32 s10, s10, s11
	s_cmp_le_i32 s10, s30
	s_cselect_b64 s[16:17], -1, 0
	s_and_b64 vcc, exec, s[16:17]
	s_setprio 0
	s_waitcnt lgkmcnt(0)
	v_mfma_f32_32x32x16_bf16 v[36:51], v[36:39], v[84:87], 0
	ds_read_b128 v[68:71], v1 offset:6688
	v_lshl_add_u64 v[72:73], v[136:137], 0, s[74:75]
	v_lshlrev_b64 v[72:73], 6, v[72:73]
	v_lshl_add_u64 v[72:73], v[140:141], 0, v[72:73]
	v_lshl_add_u64 v[72:73], v[72:73], 0, s[12:13]
	v_mfma_f32_32x32x16_bf16 v[36:51], v[52:55], v[88:91], v[36:51]
	ds_read_b128 v[52:55], v1 offset:64
	v_lshl_add_u64 v[74:75], s[20:21], 0, v[146:147]
	v_lshl_add_u64 v[74:75], v[74:75], 0, s[100:101]
	v_cndmask_b32_e64 v72, v74, v72, s[44:45]
	v_cndmask_b32_e64 v73, v75, v73, s[44:45]
	s_waitcnt lgkmcnt(0)
	v_mfma_f32_32x32x16_bf16 v[36:51], v[52:55], v[92:95], v[36:51]
	global_load_dwordx4 v[108:111], v[72:73], off
	ds_read_b128 v[52:55], v1 offset:96
	v_lshl_add_u64 v[72:73], v[138:139], 0, s[74:75]
	v_lshlrev_b64 v[72:73], 6, v[72:73]
	v_lshl_add_u64 v[72:73], v[142:143], 0, v[72:73]
	v_lshl_add_u64 v[72:73], v[72:73], 0, s[12:13]
	s_waitcnt lgkmcnt(0)
	v_mfma_f32_32x32x16_bf16 v[36:51], v[52:55], v[96:99], v[36:51]
	ds_read_b128 v[52:55], v1 offset:128
	v_lshl_add_u64 v[74:75], s[20:21], 0, v[148:149]
	v_lshl_add_u64 v[74:75], v[74:75], 0, s[100:101]
	v_cndmask_b32_e64 v72, v74, v72, s[46:47]
	v_cndmask_b32_e64 v73, v75, v73, s[46:47]
	s_waitcnt lgkmcnt(0)
	v_mfma_f32_32x32x16_bf16 v[36:51], v[52:55], v[100:103], v[36:51]
	ds_read_b128 v[52:55], v1 offset:160
	s_cmp_eq_u64 s[42:43], 0
	s_cbranch_scc1 .Lmla_c2s1
	global_load_dwordx4 v[112:115], v[72:73], off
.Lmla_c2s1:
	v_lshl_add_u64 v[74:75], s[20:21], 0, v[144:145]
	s_mov_b64 s[12:13], 0x28100000
	v_lshl_add_u64 v[74:75], v[74:75], 0, s[12:13]
	s_waitcnt lgkmcnt(0)
	v_mfma_f32_32x32x16_bf16 v[36:51], v[52:55], v[104:107], v[36:51]
	global_load_dwordx4 v[116:119], v[74:75], off offset:256
	ds_read_b128 v[52:55], v1 offset:6656
	s_waitcnt lgkmcnt(0)
	v_mfma_f32_32x32x16_bf16 v[52:67], v[52:55], v[84:87], 0
	v_mfma_f32_32x32x16_bf16 v[52:67], v[68:71], v[88:91], v[52:67]
	ds_read_b128 v[68:71], v1 offset:6720
	s_waitcnt lgkmcnt(0)
	v_mfma_f32_32x32x16_bf16 v[52:67], v[68:71], v[92:95], v[52:67]
	ds_read_b128 v[68:71], v1 offset:6752
	s_waitcnt lgkmcnt(0)
	v_mfma_f32_32x32x16_bf16 v[52:67], v[68:71], v[96:99], v[52:67]
	ds_read_b128 v[68:71], v1 offset:6784
	s_waitcnt lgkmcnt(0)
	v_mfma_f32_32x32x16_bf16 v[52:67], v[68:71], v[100:103], v[52:67]
	ds_read_b128 v[68:71], v1 offset:6816
	s_waitcnt lgkmcnt(0)
	v_mfma_f32_32x32x16_bf16 v[52:67], v[68:71], v[104:107], v[52:67]
	s_setprio 1
	s_cbranch_vccnz .LBB0_1019
	s_branch .Lmla_m1
.Lmla_qkp1:
	s_add_i32 s10, s49, 0xffffffa0
	s_sub_i32 s11, s49, 64
	s_max_i32 s10, s10, s11
	s_setprio 0
	s_waitcnt lgkmcnt(0)
	v_mfma_f32_32x32x16_bf16 v[36:51], v[36:39], v[84:87], 0
	s_cmp_le_i32 s10, s30
	s_cselect_b64 s[16:17], -1, 0
	s_and_b64 vcc, exec, s[16:17]
	ds_read_b128 v[68:71], v1 offset:6688
	v_mfma_f32_32x32x16_bf16 v[36:51], v[52:55], v[88:91], v[36:51]
	ds_read_b128 v[52:55], v1 offset:64
	s_waitcnt lgkmcnt(0)
	v_mfma_f32_32x32x16_bf16 v[36:51], v[52:55], v[92:95], v[36:51]
	ds_read_b128 v[52:55], v1 offset:96
	s_waitcnt lgkmcnt(0)
	v_mfma_f32_32x32x16_bf16 v[36:51], v[52:55], v[96:99], v[36:51]
	ds_read_b128 v[52:55], v1 offset:128
	s_waitcnt lgkmcnt(0)
	v_mfma_f32_32x32x16_bf16 v[36:51], v[52:55], v[100:103], v[36:51]
	ds_read_b128 v[52:55], v1 offset:160
	s_waitcnt lgkmcnt(0)
	v_mfma_f32_32x32x16_bf16 v[36:51], v[52:55], v[104:107], v[36:51]
	ds_read_b128 v[52:55], v1 offset:6656
	s_waitcnt lgkmcnt(0)
	v_mfma_f32_32x32x16_bf16 v[52:67], v[52:55], v[84:87], 0
	v_mfma_f32_32x32x16_bf16 v[52:67], v[68:71], v[88:91], v[52:67]
	ds_read_b128 v[68:71], v1 offset:6720
	s_waitcnt lgkmcnt(0)
	v_mfma_f32_32x32x16_bf16 v[52:67], v[68:71], v[92:95], v[52:67]
	ds_read_b128 v[68:71], v1 offset:6752
	s_waitcnt lgkmcnt(0)
	v_mfma_f32_32x32x16_bf16 v[52:67], v[68:71], v[96:99], v[52:67]
	ds_read_b128 v[68:71], v1 offset:6784
	s_waitcnt lgkmcnt(0)
	v_mfma_f32_32x32x16_bf16 v[52:67], v[68:71], v[100:103], v[52:67]
	ds_read_b128 v[68:71], v1 offset:6816
	s_waitcnt lgkmcnt(0)
	v_mfma_f32_32x32x16_bf16 v[52:67], v[68:71], v[104:107], v[52:67]
	s_setprio 1
	s_cbranch_vccnz .LBB0_1019

; __device__ __forceinline__ unsigned cvt_pk_bf16(float lo, float hi) { unsigned r; asm volatile("v_cvt_pk_bf16_f32 %0, %1, %2" : "=v"(r) : "v"(lo), "v"(hi)); return r; }
; #define LAS __attribute__((address_space(3)))
; __device__ __forceinline__ float fast_exp2(float x) { return __builtin_amdgcn_exp2f(x); }
; template <int DV32>
; __device__ __forceinline__ void pv_sub(f32x16 (&o)[DV32], const LAS unsigned char* Vt, int vs, int sub, const f32x16& p, int r32, int hi) {
; #pragma unroll
;     for (int kb = 0; kb < 2; ++kb) {
;         u32x4 pw; pw.x = cvt_pk_bf16(p[8 * kb + 0], p[8 * kb + 1]); pw.y = cvt_pk_bf16(p[8 * kb + 2], p[8 * kb + 3]); pw.z = cvt_pk_bf16(p[8 * kb + 4], p[8 * kb + 5]); pw.w = cvt_pk_bf16(p[8 * kb + 6], p[8 * kb + 7]);
;         const bf16x8 pf = __builtin_bit_cast(bf16x8, pw);
; #pragma unroll
;         for (int i = 0; i < DV32; ++i) {
;             const bf16x8 vf = *(const LAS bf16x8*)(Vt + (32 * i + r32) * vs + sub * 64 + kb * 32 + hi * 16);
;             o[i] = __builtin_amdgcn_mfma_f32_32x32x16_bf16(vf, pf, o[i], 0, 0, 0);
;         }
;     }
; }
; template <int D, int DV, int MODE, bool HASBIAS, bool JOINT, bool DEFER, class KA, class VA, class PF, class BF, class VF, class NM, class WS, class CB> ...
;     ...
;                 for (int v = 0; v < 16; ++v) { const float p0 = fast_exp2(s0[v] - mn), p1 = fast_exp2(s1[v] - mn); s0[v] = p0; s1[v] = p1; sum0 += p0; sum1 += p1; }
;             }
;             if (grow) {
;                 const float alpha = fast_exp2(m - mn); l *= alpha;
;                 if (MODE == 0) {
; #pragma unroll
;                     for (int i = 0; i < DV / 32; ++i)
; #pragma unroll
;                         for (int v = 0; v < 16; ++v) o[i][v] *= alpha;
;                 }
;             }
;             l += sum0 + sum1; m = mn;
;             if (MODE == 0) {
;                 if (defer_wave) { pp0 = pack8(s0, 0); pp1 = pack8(s0, 1); pp2 = pack8(s1, 0); pp3 = pack8(s1, 1); pend = vslot; }
;                 else { pv_sub<DV / 32>(o, curv, VS, 0, s0, r32, hi); pv_sub<DV / 32>(o, curv, VS, 1, s1, r32, hi); }
.Lmla_es1_done:
	v_add_u32_e32 v1, v175, v184
	v_cvt_pk_bf16_f32 v194, v151, v157
	v_cvt_pk_bf16_f32 v195, v153, v161
	ds_read_b128 v[198:201], v1 offset:26624
	ds_read_b128 v[48:51], v1 offset:31232
	v_cvt_pk_bf16_f32 v196, v155, v165
	v_cvt_pk_bf16_f32 v197, v159, v167
	s_mov_b64 s[10:11], 0
	v_add_f32_e32 v168, 0, v150
	v_add_f32_e32 v169, 0, v151
	v_cvt_pk_bf16_f32 v36, v69, v75
	v_add_f32_e32 v168, v156, v168
	v_add_f32_e32 v169, v157, v169
	s_setprio 0
	s_waitcnt lgkmcnt(1)
	v_mfma_f32_32x32x16_bf16 v[4:19], v[198:201], v[194:197], v[4:19]
	ds_read_b128 v[52:55], v1 offset:26656
	ds_read_b128 v[56:59], v1 offset:31264
	v_cvt_pk_bf16_f32 v37, v71, v79
	v_add_f32_e32 v168, v152, v168
	v_add_f32_e32 v169, v153, v169
	v_cvt_pk_bf16_f32 v38, v73, v81
	v_add_f32_e32 v168, v160, v168
	v_add_f32_e32 v169, v161, v169
	s_waitcnt lgkmcnt(2)
	v_mfma_f32_32x32x16_bf16 v[20:35], v[48:51], v[194:197], v[20:35]
	v_cvt_pk_bf16_f32 v39, v77, v83
	v_add_f32_e32 v168, v154, v168
	v_add_f32_e32 v169, v155, v169
	v_cvt_pk_bf16_f32 v40, v150, v156
	v_add_f32_e32 v168, v164, v168
	v_add_f32_e32 v169, v165, v169
	s_waitcnt lgkmcnt(1)
	v_mfma_f32_32x32x16_bf16 v[4:19], v[52:55], v[36:39], v[4:19]
	ds_read_b128 v[60:63], v1 offset:26688
	ds_read_b128 v[64:67], v1 offset:31296
	v_cvt_pk_bf16_f32 v41, v152, v160
	v_add_f32_e32 v168, v158, v168
	v_add_f32_e32 v169, v159, v169
	v_cvt_pk_bf16_f32 v42, v154, v164
	v_add_f32_e32 v168, v166, v168
	v_add_f32_e32 v169, v167, v169
	s_waitcnt lgkmcnt(2)
	v_mfma_f32_32x32x16_bf16 v[20:35], v[56:59], v[36:39], v[20:35]
	v_cvt_pk_bf16_f32 v43, v158, v166
	v_add_f32_e32 v168, v68, v168
	v_add_f32_e32 v169, v69, v169
	v_cvt_pk_bf16_f32 v44, v68, v74
	v_add_f32_e32 v168, v74, v168
	v_add_f32_e32 v169, v75, v169
	s_waitcnt lgkmcnt(1)
	v_mfma_f32_32x32x16_bf16 v[4:19], v[60:63], v[40:43], v[4:19]
	ds_read_b128 v[198:201], v1 offset:26720
	ds_read_b128 v[48:51], v1 offset:31328
	v_cvt_pk_bf16_f32 v45, v70, v78
	v_add_f32_e32 v168, v70, v168
	v_add_f32_e32 v169, v71, v169
	v_cvt_pk_bf16_f32 v46, v72, v80
	v_add_f32_e32 v168, v78, v168
	v_add_f32_e32 v169, v79, v169
	s_waitcnt lgkmcnt(2)
	v_mfma_f32_32x32x16_bf16 v[20:35], v[64:67], v[40:43], v[20:35]
	v_cvt_pk_bf16_f32 v47, v76, v82
	v_add_f32_e32 v168, v72, v168
	v_add_f32_e32 v169, v73, v169
	v_add_f32_e32 v168, v80, v168
	v_add_f32_e32 v169, v81, v169
	s_waitcnt lgkmcnt(1)
	v_mfma_f32_32x32x16_bf16 v[4:19], v[198:201], v[44:47], v[4:19]
	v_add_f32_e32 v168, v76, v168
	v_add_f32_e32 v169, v77, v169
	v_add_f32_e32 v168, v82, v168
	v_add_f32_e32 v169, v83, v169
	s_waitcnt lgkmcnt(0)
	v_mfma_f32_32x32x16_bf16 v[20:35], v[48:51], v[44:47], v[20:35]
	s_setprio 1
	v_add_f32_e32 v168, v168, v169
	v_add_f32_e32 v192, v168, v192
	s_add_i32 s10, s48, -2
	s_cmp_lt_u32 s10, s38
	s_cselect_b64 s[8:9], -1, 0
	s_branch .LBB0_1057

; #define LAS __attribute__((address_space(3)))
; template <int DK16>
; __device__ __forceinline__ f32x16 qk_sub(const LAS unsigned char* Kt, int ks, int sub, const bf16x8 (&qf)[DK16], int r32, int hi) {
;     f32x16 s;
; #pragma unroll
;     for (int v = 0; v < 16; ++v) s[v] = 0.f;
;     const LAS unsigned char* p = Kt + (sub * 32 + r32) * ks + hi * 16;
; #pragma unroll
;     for (int dk = 0; dk < DK16; ++dk) { const bf16x8 kf = *(const LAS bf16x8*)(p + dk * 32); s = __builtin_amdgcn_mfma_f32_32x32x16_bf16(kf, qf[dk], s, 0, 0, 0); }
;     return s;
; }
; template <int D, int DV, int MODE, bool HASBIAS, bool JOINT, bool DEFER, class KA, class VA, class PF, class BF, class VF, class NM, class WS, class CB> ...
;     ...
;         const bool sk0 = wskip(t, 0), sk1 = wskip(t, 1);
;         if (JOINT && MODE != 2 && !sk0 && !sk1) {
;             f32x16 s0 = qk_sub<D / 16>(cur, KS, 0, qf, r32, hi); if (DEFER) __builtin_amdgcn_sched_barrier(0); f32x16 s1 = qk_sub<D / 16>(cur, KS, 1, qf, r32, hi);
.LBB0_1072:
	s_sub_i32 s10, s49, 63
	s_cmp_le_i32 s10, s39
	s_cselect_b64 s[8:9], -1, 0
	s_sub_i32 s11, s49, 31
	s_cmp_le_i32 s11, s39
	s_cselect_b64 s[18:19], -1, 0
	s_max_i32 s10, s10, s11
	s_cmp_gt_i32 s10, s39
	s_cselect_b64 s[10:11], -1, 0
	s_andn2_b64 vcc, exec, s[10:11]
	s_cbranch_vccz .LBB0_1084
	v_add_u32_e32 v1, v173, v2
	ds_read_b128 v[36:39], v1 offset:13312
	ds_read_b128 v[52:55], v1 offset:13344
	s_cmp_ge_u32 s48, s38
	s_cbranch_scc1 .Lmla_qkp2
	s_lshl_b32 s74, s54, 6
	s_add_i32 s74, s74, 0xc0
	s_mov_b64 s[12:13], 0x340fff80
	s_mov_b64 s[100:101], 0x24130000
	s_sub_i32 s10, s49, 32
	s_max_i32 s10, s10, s49
	s_cmp_le_i32 s10, s30
	s_cselect_b64 s[16:17], -1, 0
	s_and_b64 vcc, exec, s[16:17]
	s_setprio 0
	s_waitcnt lgkmcnt(0)
	v_mfma_f32_32x32x16_bf16 v[36:51], v[36:39], v[84:87], 0
	ds_read_b128 v[68:71], v1 offset:20000
	v_lshl_add_u64 v[72:73], v[136:137], 0, s[74:75]
	v_lshlrev_b64 v[72:73], 6, v[72:73]
	v_lshl_add_u64 v[72:73], v[140:141], 0, v[72:73]
	v_lshl_add_u64 v[72:73], v[72:73], 0, s[12:13]
	v_mfma_f32_32x32x16_bf16 v[36:51], v[52:55], v[88:91], v[36:51]
	ds_read_b128 v[52:55], v1 offset:13376
	v_lshl_add_u64 v[74:75], s[20:21], 0, v[146:147]
	v_lshl_add_u64 v[74:75], v[74:75], 0, s[100:101]
	v_cndmask_b32_e64 v72, v74, v72, s[44:45]
	v_cndmask_b32_e64 v73, v75, v73, s[44:45]
	s_waitcnt lgkmcnt(0)
	v_mfma_f32_32x32x16_bf16 v[36:51], v[52:55], v[92:95], v[36:51]
	global_load_dwordx4 v[120:123], v[72:73], off
	ds_read_b128 v[52:55], v1 offset:13408
	v_lshl_add_u64 v[72:73], v[138:139], 0, s[74:75]
	v_lshlrev_b64 v[72:73], 6, v[72:73]
	v_lshl_add_u64 v[72:73], v[142:143], 0, v[72:73]
	v_lshl_add_u64 v[72:73], v[72:73], 0, s[12:13]
	s_waitcnt lgkmcnt(0)
	v_mfma_f32_32x32x16_bf16 v[36:51], v[52:55], v[96:99], v[36:51]
	ds_read_b128 v[52:55], v1 offset:13440
	v_lshl_add_u64 v[74:75], s[20:21], 0, v[148:149]
	v_lshl_add_u64 v[74:75], v[74:75], 0, s[100:101]
	v_cndmask_b32_e64 v72, v74, v72, s[46:47]
	v_cndmask_b32_e64 v73, v75, v73, s[46:47]
	s_waitcnt lgkmcnt(0)
	v_mfma_f32_32x32x16_bf16 v[36:51], v[52:55], v[100:103], v[36:51]
	ds_read_b128 v[52:55], v1 offset:13472
	s_cmp_eq_u64 s[42:43], 0
	s_cbranch_scc1 .Lmla_c2s2
	global_load_dwordx4 v[124:127], v[72:73], off
.Lmla_c2s2:
	v_lshl_add_u64 v[74:75], s[20:21], 0, v[144:145]
	s_mov_b64 s[12:13], 0x28100000
	v_lshl_add_u64 v[74:75], v[74:75], 0, s[12:13]
	s_waitcnt lgkmcnt(0)
	v_mfma_f32_32x32x16_bf16 v[36:51], v[52:55], v[104:107], v[36:51]
	global_load_dwordx4 v[128:131], v[74:75], off offset:384
	ds_read_b128 v[52:55], v1 offset:19968
	s_waitcnt lgkmcnt(0)
	v_mfma_f32_32x32x16_bf16 v[52:67], v[52:55], v[84:87], 0
	v_mfma_f32_32x32x16_bf16 v[52:67], v[68:71], v[88:91], v[52:67]
	ds_read_b128 v[68:71], v1 offset:20032
	s_waitcnt lgkmcnt(0)
	v_mfma_f32_32x32x16_bf16 v[52:67], v[68:71], v[92:95], v[52:67]
	ds_read_b128 v[68:71], v1 offset:20064
	s_waitcnt lgkmcnt(0)
	v_mfma_f32_32x32x16_bf16 v[52:67], v[68:71], v[96:99], v[52:67]
	ds_read_b128 v[68:71], v1 offset:20096
	s_waitcnt lgkmcnt(0)
	v_mfma_f32_32x32x16_bf16 v[52:67], v[68:71], v[100:103], v[52:67]
	ds_read_b128 v[68:71], v1 offset:20128
	s_waitcnt lgkmcnt(0)
	v_mfma_f32_32x32x16_bf16 v[52:67], v[68:71], v[104:107], v[52:67]
	s_setprio 1
	s_cbranch_vccnz .LBB0_1075
	s_branch .Lmla_m2
.Lmla_qkp2:
	s_sub_i32 s10, s49, 32
	s_max_i32 s10, s10, s49
	s_cmp_le_i32 s10, s30
	s_setprio 0
	s_waitcnt lgkmcnt(0)
	v_mfma_f32_32x32x16_bf16 v[36:51], v[36:39], v[84:87], 0
	s_cselect_b64 s[16:17], -1, 0
	s_and_b64 vcc, exec, s[16:17]
	ds_read_b128 v[68:71], v1 offset:20000
	v_mfma_f32_32x32x16_bf16 v[36:51], v[52:55], v[88:91], v[36:51]
	ds_read_b128 v[52:55], v1 offset:13376
	s_waitcnt lgkmcnt(0)
	v_mfma_f32_32x32x16_bf16 v[36:51], v[52:55], v[92:95], v[36:51]
	ds_read_b128 v[52:55], v1 offset:13408
	s_waitcnt lgkmcnt(0)
	v_mfma_f32_32x32x16_bf16 v[36:51], v[52:55], v[96:99], v[36:51]
	ds_read_b128 v[52:55], v1 offset:13440
	s_waitcnt lgkmcnt(0)
	v_mfma_f32_32x32x16_bf16 v[36:51], v[52:55], v[100:103], v[36:51]
	ds_read_b128 v[52:55], v1 offset:13472
	s_waitcnt lgkmcnt(0)
	v_mfma_f32_32x32x16_bf16 v[36:51], v[52:55], v[104:107], v[36:51]
	ds_read_b128 v[52:55], v1 offset:19968
	s_waitcnt lgkmcnt(0)
	v_mfma_f32_32x32x16_bf16 v[52:67], v[52:55], v[84:87], 0
	v_mfma_f32_32x32x16_bf16 v[52:67], v[68:71], v[88:91], v[52:67]
	ds_read_b128 v[68:71], v1 offset:20032
	s_waitcnt lgkmcnt(0)
	v_mfma_f32_32x32x16_bf16 v[52:67], v[68:71], v[92:95], v[52:67]
	ds_read_b128 v[68:71], v1 offset:20064
	s_waitcnt lgkmcnt(0)
	v_mfma_f32_32x32x16_bf16 v[52:67], v[68:71], v[96:99], v[52:67]
	ds_read_b128 v[68:71], v1 offset:20096
	s_waitcnt lgkmcnt(0)
	v_mfma_f32_32x32x16_bf16 v[52:67], v[68:71], v[100:103], v[52:67]
	ds_read_b128 v[68:71], v1 offset:20128
	s_waitcnt lgkmcnt(0)
	v_mfma_f32_32x32x16_bf16 v[52:67], v[68:71], v[104:107], v[52:67]
	s_setprio 1
	s_cbranch_vccnz .LBB0_1075

; __device__ __forceinline__ unsigned cvt_pk_bf16(float lo, float hi) { unsigned r; asm volatile("v_cvt_pk_bf16_f32 %0, %1, %2" : "=v"(r) : "v"(lo), "v"(hi)); return r; }
; #define LAS __attribute__((address_space(3)))
; __device__ __forceinline__ float fast_exp2(float x) { return __builtin_amdgcn_exp2f(x); }
; template <int DV32>
; __device__ __forceinline__ void pv_sub(f32x16 (&o)[DV32], const LAS unsigned char* Vt, int vs, int sub, const f32x16& p, int r32, int hi) {
; #pragma unroll
;     for (int kb = 0; kb < 2; ++kb) {
;         u32x4 pw; pw.x = cvt_pk_bf16(p[8 * kb + 0], p[8 * kb + 1]); pw.y = cvt_pk_bf16(p[8 * kb + 2], p[8 * kb + 3]); pw.z = cvt_pk_bf16(p[8 * kb + 4], p[8 * kb + 5]); pw.w = cvt_pk_bf16(p[8 * kb + 6], p[8 * kb + 7]);
;         const bf16x8 pf = __builtin_bit_cast(bf16x8, pw);
; #pragma unroll
;         for (int i = 0; i < DV32; ++i) {
;             const bf16x8 vf = *(const LAS bf16x8*)(Vt + (32 * i + r32) * vs + sub * 64 + kb * 32 + hi * 16);
;             o[i] = __builtin_amdgcn_mfma_f32_32x32x16_bf16(vf, pf, o[i], 0, 0, 0);
;         }
;     }
; }
; template <int D, int DV, int MODE, bool HASBIAS, bool JOINT, bool DEFER, class KA, class VA, class PF, class BF, class VF, class NM, class WS, class CB> ...
;     ...
;                 for (int v = 0; v < 16; ++v) { const float p0 = fast_exp2(s0[v] - mn), p1 = fast_exp2(s1[v] - mn); s0[v] = p0; s1[v] = p1; sum0 += p0; sum1 += p1; }
;             }
;             if (grow) {
;                 const float alpha = fast_exp2(m - mn); l *= alpha;
;                 if (MODE == 0) {
; #pragma unroll
;                     for (int i = 0; i < DV / 32; ++i)
; #pragma unroll
;                         for (int v = 0; v < 16; ++v) o[i][v] *= alpha;
;                 }
;             }
;             l += sum0 + sum1; m = mn;
;             if (MODE == 0) {
;                 if (defer_wave) { pp0 = pack8(s0, 0); pp1 = pack8(s0, 1); pp2 = pack8(s1, 0); pp3 = pack8(s1, 1); pend = vslot; }
;                 else { pv_sub<DV / 32>(o, curv, VS, 0, s0, r32, hi); pv_sub<DV / 32>(o, curv, VS, 1, s1, r32, hi); }
.Lmla_es2_done:
	v_add_u32_e32 v1, v175, v184
	v_cvt_pk_bf16_f32 v194, v151, v157
	v_cvt_pk_bf16_f32 v195, v153, v161
	ds_read_b128 v[198:201], v1 offset:35840
	ds_read_b128 v[48:51], v1 offset:40448
	v_cvt_pk_bf16_f32 v196, v155, v165
	v_cvt_pk_bf16_f32 v197, v159, v167
	s_mov_b64 s[10:11], 0
	v_add_f32_e32 v168, 0, v150
	v_add_f32_e32 v169, 0, v151
	v_cvt_pk_bf16_f32 v36, v69, v75
	v_add_f32_e32 v168, v156, v168
	v_add_f32_e32 v169, v157, v169
	s_setprio 0
	s_waitcnt lgkmcnt(1)
	v_mfma_f32_32x32x16_bf16 v[4:19], v[198:201], v[194:197], v[4:19]
	ds_read_b128 v[52:55], v1 offset:35872
	ds_read_b128 v[56:59], v1 offset:40480
	v_cvt_pk_bf16_f32 v37, v71, v79
	v_add_f32_e32 v168, v152, v168
	v_add_f32_e32 v169, v153, v169
	v_cvt_pk_bf16_f32 v38, v73, v81
	v_add_f32_e32 v168, v160, v168
	v_add_f32_e32 v169, v161, v169
	s_waitcnt lgkmcnt(2)
	v_mfma_f32_32x32x16_bf16 v[20:35], v[48:51], v[194:197], v[20:35]
	v_cvt_pk_bf16_f32 v39, v77, v83
	v_add_f32_e32 v168, v154, v168
	v_add_f32_e32 v169, v155, v169
	v_cvt_pk_bf16_f32 v40, v150, v156
	v_add_f32_e32 v168, v164, v168
	v_add_f32_e32 v169, v165, v169
	s_waitcnt lgkmcnt(1)
	v_mfma_f32_32x32x16_bf16 v[4:19], v[52:55], v[36:39], v[4:19]
	ds_read_b128 v[60:63], v1 offset:35904
	ds_read_b128 v[64:67], v1 offset:40512
	v_cvt_pk_bf16_f32 v41, v152, v160
	v_add_f32_e32 v168, v158, v168
	v_add_f32_e32 v169, v159, v169
	v_cvt_pk_bf16_f32 v42, v154, v164
	v_add_f32_e32 v168, v166, v168
	v_add_f32_e32 v169, v167, v169
	s_waitcnt lgkmcnt(2)
	v_mfma_f32_32x32x16_bf16 v[20:35], v[56:59], v[36:39], v[20:35]
	v_cvt_pk_bf16_f32 v43, v158, v166
	v_add_f32_e32 v168, v68, v168
	v_add_f32_e32 v169, v69, v169
	v_cvt_pk_bf16_f32 v44, v68, v74
	v_add_f32_e32 v168, v74, v168
	v_add_f32_e32 v169, v75, v169
	s_waitcnt lgkmcnt(1)
	v_mfma_f32_32x32x16_bf16 v[4:19], v[60:63], v[40:43], v[4:19]
	ds_read_b128 v[198:201], v1 offset:35936
	ds_read_b128 v[48:51], v1 offset:40544
	v_cvt_pk_bf16_f32 v45, v70, v78
	v_add_f32_e32 v168, v70, v168
	v_add_f32_e32 v169, v71, v169
	v_cvt_pk_bf16_f32 v46, v72, v80
	v_add_f32_e32 v168, v78, v168
	v_add_f32_e32 v169, v79, v169
	s_waitcnt lgkmcnt(2)
	v_mfma_f32_32x32x16_bf16 v[20:35], v[64:67], v[40:43], v[20:35]
	v_cvt_pk_bf16_f32 v47, v76, v82
	v_add_f32_e32 v168, v72, v168
	v_add_f32_e32 v169, v73, v169
	v_add_f32_e32 v168, v80, v168
	v_add_f32_e32 v169, v81, v169
	s_waitcnt lgkmcnt(1)
	v_mfma_f32_32x32x16_bf16 v[4:19], v[198:201], v[44:47], v[4:19]
	v_add_f32_e32 v168, v76, v168
	v_add_f32_e32 v169, v77, v169
	v_add_f32_e32 v168, v82, v168
	v_add_f32_e32 v169, v83, v169
	s_waitcnt lgkmcnt(0)
	v_mfma_f32_32x32x16_bf16 v[20:35], v[48:51], v[44:47], v[20:35]
	s_setprio 1
	v_add_f32_e32 v168, v168, v169
	v_add_f32_e32 v191, v168, v191
	s_branch .LBB0_1114
